# MLP-up GEMM phase: every second workgroup of each XCD starts ~7 us late so the epilogue store bursts of the two halves alternate (stagger by workgroup-index bit 3)
# speedup vs baseline: 1.0055x; 1.0051x over previous
.LBB0_1168:
	s_or_b64 exec, exec, s[50:51]
	s_waitcnt lgkmcnt(0)
	s_barrier
	s_bfe_u32 s100, s86, 0x10003
	s_cmp_eq_u32 s100, 0
	s_cbranch_scc1 .Lstc_skip1
	s_mul_i32 s100, s100, 2
.Lstc_loop1:
	s_sleep 127
	s_sub_u32 s100, s100, 1
	s_cmp_lg_u32 s100, 0
	s_cbranch_scc1 .Lstc_loop1
.Lstc_skip1:
	v_mbcnt_lo_u32_b32 v0, -1, 0
	v_mbcnt_hi_u32_b32 v0, -1, v0
	s_mov_b32 s4, 0x1fffe0
	v_add_u32_e32 v14, s33, v0
	s_lshl_b64 s[46:47], s[64:65], 23
	v_ashrrev_i32_e32 v1, 31, v14
	v_lshrrev_b32_e32 v1, 26, v1
	v_add_u32_e32 v1, v14, v1
	v_ashrrev_i32_e32 v8, 6, v1
	v_bfe_i32 v1, v14, 27, 1
	v_lshlrev_b32_e32 v0, 4, v14
	v_lshrrev_b32_e32 v1, 22, v1
	v_add_u32_e32 v1, v0, v1
	v_and_b32_e32 v1, 0xfffffc00, v1
	v_sub_u32_e32 v1, v0, v1
	v_lshrrev_b32_e32 v2, 4, v1
	v_bitop3_b32 v1, v2, v1, 32 bitop3:0x6c
	v_ashrrev_i32_e32 v3, 31, v1
	v_lshrrev_b32_e32 v3, 26, v3
	v_add_u32_e32 v3, v1, v3
	v_lshlrev_b32_e32 v2, 3, v8
	v_ashrrev_i32_e32 v9, 6, v3
	v_and_b32_e32 v3, 0xc0, v3
	v_and_b32_e32 v2, -16, v2
	v_sub_u32_e32 v1, v1, v3
	v_add_u32_e32 v2, v9, v2
	v_ashrrev_i16_sdwa v1, v229, sext(v1) dst_sel:DWORD dst_unused:UNUSED_PAD src0_sel:DWORD src1_sel:BYTE_0
	v_lshlrev_b32_e32 v4, 5, v8
	v_bfe_i32 v10, v1, 0, 16
	v_lshlrev_b32_e32 v1, 1, v2
	v_lshrrev_b32_e32 v3, 2, v2
	v_and_b32_e32 v5, 3, v9
	v_and_b32_e32 v4, 32, v4
	v_and_b32_e32 v1, 24, v1
	v_and_b32_e32 v3, 4, v3
	v_and_or_b32 v5, v2, s4, v5
	v_or3_b32 v1, v5, v3, v1
	v_add_lshl_u32 v3, v4, v10, 1
	v_add_u32_e32 v0, 0x2000, v0
	v_lshl_add_u32 v152, v1, 11, v3
	v_ashrrev_i32_e32 v1, 31, v0
	v_lshrrev_b32_e32 v1, 22, v1
	v_add_u32_e32 v1, v0, v1
	v_ashrrev_i32_e32 v11, 10, v1
	v_mul_i32_i24_e32 v1, 0x400, v11
	v_sub_u32_e32 v0, v0, v1
	v_lshrrev_b32_e32 v1, 4, v0
	v_bitop3_b32 v0, v1, v0, 32 bitop3:0x6c
	v_lshl_add_u32 v144, v2, 11, v3
	v_ashrrev_i32_e32 v2, 31, v0
	v_lshrrev_b32_e32 v2, 26, v2
	v_lshlrev_b32_e32 v1, 3, v11
	v_add_u32_e32 v2, v0, v2
	v_readlane_b32 s2, v253, 50
	v_and_b32_e32 v1, -16, v1
	v_ashrrev_i32_e32 v12, 6, v2
	v_readlane_b32 s3, v253, 51
	s_add_u32 s24, s2, s46
	v_add_u32_e32 v1, v12, v1
	v_and_b32_e32 v4, 3, v12
	s_addc_u32 s25, s3, s47
	v_and_or_b32 v4, v1, s4, v4
	s_lshl_b32 s27, s40, 1
	v_readlane_b32 s4, v254, 8
	s_mul_i32 s4, s27, s4
	s_lshr_b32 s5, s4, 4
	s_and_b32 s4, s4, 0x60
	v_readfirstlane_b32 s2, v14
	s_and_b32 s5, s5, 0x78
	s_or_b32 s4, s4, s53
	v_readlane_b32 s6, v255, 7
	v_and_b32_e32 v2, 0xc0, v2
	s_ashr_i32 s7, s2, 6
	s_or_b32 s56, s6, s5
	s_lshr_b32 s89, s4, 3
	s_ashr_i32 s3, s2, 8
	v_sub_u32_e32 v0, v0, v2
	s_lshl_b32 s26, s7, 10
	s_lshl_b32 s6, s56, 19
	s_lshl_b32 s4, s89, 19
	v_ashrrev_i16_sdwa v0, v229, sext(v0) dst_sel:DWORD dst_unused:UNUSED_PAD src0_sel:DWORD src1_sel:BYTE_0
	s_add_u32 s20, s24, s4
	v_lshlrev_b32_e32 v3, 5, v11
	v_bfe_i32 v13, v0, 0, 16
	v_lshlrev_b32_e32 v0, 1, v1
	v_lshrrev_b32_e32 v2, 2, v1
	s_addc_u32 s21, s25, 0
	s_add_i32 s28, s26, 0
	v_and_b32_e32 v3, 32, v3
	v_and_b32_e32 v0, 24, v0
	v_and_b32_e32 v2, 4, v2
	s_add_i32 m0, s28, 0x10000
	v_or3_b32 v0, v4, v2, v0
	v_add_lshl_u32 v2, v3, v13, 1
	global_load_lds_dwordx4 v152, s[20:21]
	s_add_i32 m0, s28, 0x12000
	v_lshl_add_u32 v148, v0, 11, v2
	s_add_u32 s4, s20, 0x40000
	global_load_lds_dwordx4 v148, s[20:21]
	s_addc_u32 s5, s21, 0
	s_add_i32 m0, s28, 0x14000
	v_lshl_add_u32 v146, v1, 11, v2
	global_load_lds_dwordx4 v152, s[4:5]
	s_add_i32 m0, s28, 0x16000
	v_mov_b32_e32 v149, v153
	global_load_lds_dwordx4 v148, s[4:5]
	v_readlane_b32 s4, v254, 49
	v_readlane_b32 s5, v254, 50
	s_add_u32 s18, s4, s6
	s_addc_u32 s19, s5, 0
	s_add_i32 s29, s28, 0x2000
	s_mov_b32 m0, s28
	s_add_u32 s4, s18, 0x40000
	global_load_lds_dwordx4 v144, s[18:19]
	s_mov_b32 m0, s29
	s_addc_u32 s5, s19, 0
	s_add_i32 s30, s28, 0x4000
	global_load_lds_dwordx4 v146, s[18:19]
	s_mov_b32 m0, s30
	s_add_i32 s31, s28, 0x6000
	global_load_lds_dwordx4 v144, s[4:5]
	s_mov_b32 m0, s31
	v_mov_b32_e32 v145, v153
	global_load_lds_dwordx4 v146, s[4:5]
	v_mov_b32_e32 v147, v153
	s_cmp_eq_u32 s3, 1
	v_lshl_add_u64 v[6:7], s[20:21], 0, v[152:153]
	v_lshl_add_u64 v[4:5], s[20:21], 0, v[148:149]
	v_lshl_add_u64 v[0:1], s[18:19], 0, v[144:145]
	s_cselect_b64 s[4:5], -1, 0
	s_cmp_lg_u32 s3, 1
	v_lshl_add_u64 v[2:3], s[18:19], 0, v[146:147]
	s_cbranch_scc1 .LBB0_1170
	s_barrier
